# GSWI SwiGLU epilogue re-emitted with packed f32 mul/add and batched exp/rcp (same per-element op order), 479 -> 330 instructions
# speedup vs baseline: 1.0056x; 1.0056x over previous
; __device__ __forceinline__ unsigned cvt_pk_bf16(float lo, float hi) { f32x2 v = {lo, hi}; bf16x2_t b = __builtin_convertvector(v, bf16x2_t); return __builtin_bit_cast(unsigned, b); }
; __device__ __forceinline__ float silu_f(float g) { return g * __builtin_amdgcn_rcpf(1.0f + __expf(-g)); }
;     __device__ __forceinline__ void operator()(const AccT& acc, const pg8::Unit& u, int wr, int wc, int fr, int fq) const {
;         const int row0 = u.pm * 256 + wr * 64 + fr, col0 = u.pn * 128 + wc * 32 + 8 * fq;
; #pragma unroll
;         for (int ai = 0; ai < 2; ++ai)
; #pragma unroll
;             for (int m = 0; m < 4; ++m) {
;                 bf16_t* p = O + (size_t)(row0 + ai * 128 + m * 16) * DFF + col0;
;                 const f32x4 g0 = acc[ai][0][m][0], g1 = acc[ai][0][m][1], u0 = acc[ai][1][m][0], u1 = acc[ai][1][m][1];
;                 u32x4 w;
;                 w.x = cvt_pk_bf16(silu_f(g0[0]) * u0[0], silu_f(g0[1]) * u0[1]); w.y = cvt_pk_bf16(silu_f(g0[2]) * u0[2], silu_f(g0[3]) * u0[3]);
;                 w.z = cvt_pk_bf16(silu_f(g1[0]) * u1[0], silu_f(g1[1]) * u1[1]); w.w = cvt_pk_bf16(silu_f(g1[2]) * u1[2], silu_f(g1[3]) * u1[3]);
;                 *(u32x4*)p = w;
;             }
;     }
.LBB0_525:
	s_mov_b32 s68, 0xbfb8aa3b
	s_mov_b32 s69, 0xbfb8aa3b
	s_mov_b32 s70, 1.0
	s_mov_b32 s71, 1.0
	v_lshl_add_u32 v165, s46, 8, v3
	v_lshl_or_b32 v144, s45, 7, v147
	v_ashrrev_i32_e32 v145, 31, v144
	v_mov_b64_e32 v[142:143], s[4:5]
	v_mad_i64_i32 v[166:167], s[18:19], v165, s56, v[142:143]
	v_lshlrev_b64 v[144:145], 1, v[144:145]
	v_lshl_add_u64 v[166:167], v[166:167], 0, v[144:145]
	s_andn2_b64 vcc, exec, s[2:3]
	v_or_b32_e32 v186, 16, v165
	v_mad_i64_i32 v[186:187], s[18:19], v186, s56, v[142:143]
	v_lshl_add_u64 v[186:187], v[186:187], 0, v[144:145]
	v_pk_mul_f32 v[170:171], v[128:129], s[68:69]
	v_pk_mul_f32 v[172:173], v[130:131], s[68:69]
	v_pk_mul_f32 v[174:175], v[120:121], s[68:69]
	v_pk_mul_f32 v[176:177], v[122:123], s[68:69]
	v_exp_f32_e32 v170, v170
	v_exp_f32_e32 v171, v171
	v_exp_f32_e32 v172, v172
	v_exp_f32_e32 v173, v173
	v_exp_f32_e32 v174, v174
	v_exp_f32_e32 v175, v175
	v_exp_f32_e32 v176, v176
	v_exp_f32_e32 v177, v177
	v_pk_add_f32 v[170:171], v[170:171], s[70:71]
	v_pk_add_f32 v[172:173], v[172:173], s[70:71]
	v_pk_add_f32 v[174:175], v[174:175], s[70:71]
	v_pk_add_f32 v[176:177], v[176:177], s[70:71]
	v_rcp_f32_e32 v170, v170
	v_rcp_f32_e32 v171, v171
	v_rcp_f32_e32 v172, v172
	v_rcp_f32_e32 v173, v173
	v_rcp_f32_e32 v174, v174
	v_rcp_f32_e32 v175, v175
	v_rcp_f32_e32 v176, v176
	v_rcp_f32_e32 v177, v177
	v_pk_mul_f32 v[170:171], v[128:129], v[170:171]
	v_pk_mul_f32 v[172:173], v[130:131], v[172:173]
	v_pk_mul_f32 v[174:175], v[120:121], v[174:175]
	v_pk_mul_f32 v[176:177], v[122:123], v[176:177]
	v_pk_mul_f32 v[170:171], v[170:171], v[124:125]
	v_pk_mul_f32 v[172:173], v[172:173], v[126:127]
	v_pk_mul_f32 v[174:175], v[174:175], v[116:117]
	v_pk_mul_f32 v[176:177], v[176:177], v[118:119]
	v_cvt_pk_bf16_f32 v178, v170, v171
	v_cvt_pk_bf16_f32 v179, v172, v173
	v_cvt_pk_bf16_f32 v180, v174, v175
	v_cvt_pk_bf16_f32 v181, v176, v177
	global_store_dwordx4 v[166:167], v[178:181], off
	v_or_b32_e32 v188, 32, v165
	v_mad_i64_i32 v[188:189], s[18:19], v188, s56, v[142:143]
	v_lshl_add_u64 v[188:189], v[188:189], 0, v[144:145]
	v_pk_mul_f32 v[170:171], v[112:113], s[68:69]
	v_pk_mul_f32 v[172:173], v[114:115], s[68:69]
	v_pk_mul_f32 v[174:175], v[104:105], s[68:69]
	v_pk_mul_f32 v[176:177], v[106:107], s[68:69]
	v_exp_f32_e32 v170, v170
	v_exp_f32_e32 v171, v171
	v_exp_f32_e32 v172, v172
	v_exp_f32_e32 v173, v173
	v_exp_f32_e32 v174, v174
	v_exp_f32_e32 v175, v175
	v_exp_f32_e32 v176, v176
	v_exp_f32_e32 v177, v177
	v_pk_add_f32 v[170:171], v[170:171], s[70:71]
	v_pk_add_f32 v[172:173], v[172:173], s[70:71]
	v_pk_add_f32 v[174:175], v[174:175], s[70:71]
	v_pk_add_f32 v[176:177], v[176:177], s[70:71]
	v_rcp_f32_e32 v170, v170
	v_rcp_f32_e32 v171, v171
	v_rcp_f32_e32 v172, v172
	v_rcp_f32_e32 v173, v173
	v_rcp_f32_e32 v174, v174
	v_rcp_f32_e32 v175, v175
	v_rcp_f32_e32 v176, v176
	v_rcp_f32_e32 v177, v177
	v_pk_mul_f32 v[170:171], v[112:113], v[170:171]
	v_pk_mul_f32 v[172:173], v[114:115], v[172:173]
	v_pk_mul_f32 v[174:175], v[104:105], v[174:175]
	v_pk_mul_f32 v[176:177], v[106:107], v[176:177]
	v_pk_mul_f32 v[170:171], v[170:171], v[108:109]
	v_pk_mul_f32 v[172:173], v[172:173], v[110:111]
	v_pk_mul_f32 v[174:175], v[174:175], v[100:101]
	v_pk_mul_f32 v[176:177], v[176:177], v[102:103]
	v_cvt_pk_bf16_f32 v182, v170, v171
	v_cvt_pk_bf16_f32 v183, v172, v173
	v_cvt_pk_bf16_f32 v184, v174, v175
	v_cvt_pk_bf16_f32 v185, v176, v177
	global_store_dwordx4 v[186:187], v[182:185], off
	v_or_b32_e32 v190, 48, v165
	v_mad_i64_i32 v[190:191], s[18:19], v190, s56, v[142:143]
	v_lshl_add_u64 v[190:191], v[190:191], 0, v[144:145]
	v_pk_mul_f32 v[170:171], v[96:97], s[68:69]
	v_pk_mul_f32 v[172:173], v[98:99], s[68:69]
	v_pk_mul_f32 v[174:175], v[88:89], s[68:69]
	v_pk_mul_f32 v[176:177], v[90:91], s[68:69]
	v_exp_f32_e32 v170, v170
	v_exp_f32_e32 v171, v171
	v_exp_f32_e32 v172, v172
	v_exp_f32_e32 v173, v173
	v_exp_f32_e32 v174, v174
	v_exp_f32_e32 v175, v175
	v_exp_f32_e32 v176, v176
	v_exp_f32_e32 v177, v177
	v_pk_add_f32 v[170:171], v[170:171], s[70:71]
	v_pk_add_f32 v[172:173], v[172:173], s[70:71]
	v_pk_add_f32 v[174:175], v[174:175], s[70:71]
	v_pk_add_f32 v[176:177], v[176:177], s[70:71]
	v_rcp_f32_e32 v170, v170
	v_rcp_f32_e32 v171, v171
	v_rcp_f32_e32 v172, v172
	v_rcp_f32_e32 v173, v173
	v_rcp_f32_e32 v174, v174
	v_rcp_f32_e32 v175, v175
	v_rcp_f32_e32 v176, v176
	v_rcp_f32_e32 v177, v177
	v_pk_mul_f32 v[170:171], v[96:97], v[170:171]
	v_pk_mul_f32 v[172:173], v[98:99], v[172:173]
	v_pk_mul_f32 v[174:175], v[88:89], v[174:175]
	v_pk_mul_f32 v[176:177], v[90:91], v[176:177]
	v_pk_mul_f32 v[170:171], v[170:171], v[92:93]
	v_pk_mul_f32 v[172:173], v[172:173], v[94:95]
	v_pk_mul_f32 v[174:175], v[174:175], v[84:85]
	v_pk_mul_f32 v[176:177], v[176:177], v[86:87]
	v_cvt_pk_bf16_f32 v178, v170, v171
	v_cvt_pk_bf16_f32 v179, v172, v173
	v_cvt_pk_bf16_f32 v180, v174, v175
	v_cvt_pk_bf16_f32 v181, v176, v177
	global_store_dwordx4 v[188:189], v[178:181], off
	v_add_u32_e32 v192, 0x80, v165
	v_mad_i64_i32 v[192:193], s[18:19], v192, s56, v[142:143]
	v_lshl_add_u64 v[192:193], v[192:193], 0, v[144:145]
	v_pk_mul_f32 v[170:171], v[80:81], s[68:69]
	v_pk_mul_f32 v[172:173], v[82:83], s[68:69]
	v_pk_mul_f32 v[174:175], v[72:73], s[68:69]
	v_pk_mul_f32 v[176:177], v[74:75], s[68:69]
	v_exp_f32_e32 v170, v170
	v_exp_f32_e32 v171, v171
	v_exp_f32_e32 v172, v172
	v_exp_f32_e32 v173, v173
	v_exp_f32_e32 v174, v174
	v_exp_f32_e32 v175, v175
	v_exp_f32_e32 v176, v176
	v_exp_f32_e32 v177, v177
	v_pk_add_f32 v[170:171], v[170:171], s[70:71]
	v_pk_add_f32 v[172:173], v[172:173], s[70:71]
	v_pk_add_f32 v[174:175], v[174:175], s[70:71]
; __device__ __forceinline__ unsigned cvt_pk_bf16(float lo, float hi) { f32x2 v = {lo, hi}; bf16x2_t b = __builtin_convertvector(v, bf16x2_t); return __builtin_bit_cast(unsigned, b); }
; __device__ __forceinline__ float silu_f(float g) { return g * __builtin_amdgcn_rcpf(1.0f + __expf(-g)); }
;     __device__ __forceinline__ void operator()(const AccT& acc, const pg8::Unit& u, int wr, int wc, int fr, int fq) const {
;         const int row0 = u.pm * 256 + wr * 64 + fr, col0 = u.pn * 128 + wc * 32 + 8 * fq;
; #pragma unroll
;         for (int ai = 0; ai < 2; ++ai)
; #pragma unroll
;             for (int m = 0; m < 4; ++m) {
;                 bf16_t* p = O + (size_t)(row0 + ai * 128 + m * 16) * DFF + col0;
;                 const f32x4 g0 = acc[ai][0][m][0], g1 = acc[ai][0][m][1], u0 = acc[ai][1][m][0], u1 = acc[ai][1][m][1];
;                 u32x4 w;
;                 w.x = cvt_pk_bf16(silu_f(g0[0]) * u0[0], silu_f(g0[1]) * u0[1]); w.y = cvt_pk_bf16(silu_f(g0[2]) * u0[2], silu_f(g0[3]) * u0[3]);
;                 w.z = cvt_pk_bf16(silu_f(g1[0]) * u1[0], silu_f(g1[1]) * u1[1]); w.w = cvt_pk_bf16(silu_f(g1[2]) * u1[2], silu_f(g1[3]) * u1[3]);
;                 *(u32x4*)p = w;
;             }
;     }
	v_pk_add_f32 v[176:177], v[176:177], s[70:71]
	v_rcp_f32_e32 v170, v170
	v_rcp_f32_e32 v171, v171
	v_rcp_f32_e32 v172, v172
	v_rcp_f32_e32 v173, v173
	v_rcp_f32_e32 v174, v174
	v_rcp_f32_e32 v175, v175
	v_rcp_f32_e32 v176, v176
	v_rcp_f32_e32 v177, v177
	v_pk_mul_f32 v[170:171], v[80:81], v[170:171]
	v_pk_mul_f32 v[172:173], v[82:83], v[172:173]
	v_pk_mul_f32 v[174:175], v[72:73], v[174:175]
	v_pk_mul_f32 v[176:177], v[74:75], v[176:177]
	v_pk_mul_f32 v[170:171], v[170:171], v[76:77]
	v_pk_mul_f32 v[172:173], v[172:173], v[78:79]
	v_pk_mul_f32 v[174:175], v[174:175], v[68:69]
	v_pk_mul_f32 v[176:177], v[176:177], v[70:71]
	v_cvt_pk_bf16_f32 v182, v170, v171
	v_cvt_pk_bf16_f32 v183, v172, v173
	v_cvt_pk_bf16_f32 v184, v174, v175
	v_cvt_pk_bf16_f32 v185, v176, v177
	global_store_dwordx4 v[190:191], v[182:185], off
	v_add_u32_e32 v194, 0x90, v165
	v_mad_i64_i32 v[194:195], s[18:19], v194, s56, v[142:143]
	v_lshl_add_u64 v[194:195], v[194:195], 0, v[144:145]
	v_pk_mul_f32 v[170:171], v[64:65], s[68:69]
	v_pk_mul_f32 v[172:173], v[66:67], s[68:69]
	v_pk_mul_f32 v[174:175], v[56:57], s[68:69]
	v_pk_mul_f32 v[176:177], v[58:59], s[68:69]
	v_exp_f32_e32 v170, v170
	v_exp_f32_e32 v171, v171
	v_exp_f32_e32 v172, v172
	v_exp_f32_e32 v173, v173
	v_exp_f32_e32 v174, v174
	v_exp_f32_e32 v175, v175
	v_exp_f32_e32 v176, v176
	v_exp_f32_e32 v177, v177
	v_pk_add_f32 v[170:171], v[170:171], s[70:71]
	v_pk_add_f32 v[172:173], v[172:173], s[70:71]
	v_pk_add_f32 v[174:175], v[174:175], s[70:71]
	v_pk_add_f32 v[176:177], v[176:177], s[70:71]
	v_rcp_f32_e32 v170, v170
	v_rcp_f32_e32 v171, v171
	v_rcp_f32_e32 v172, v172
	v_rcp_f32_e32 v173, v173
	v_rcp_f32_e32 v174, v174
	v_rcp_f32_e32 v175, v175
	v_rcp_f32_e32 v176, v176
	v_rcp_f32_e32 v177, v177
	v_pk_mul_f32 v[170:171], v[64:65], v[170:171]
	v_pk_mul_f32 v[172:173], v[66:67], v[172:173]
	v_pk_mul_f32 v[174:175], v[56:57], v[174:175]
	v_pk_mul_f32 v[176:177], v[58:59], v[176:177]
	v_pk_mul_f32 v[170:171], v[170:171], v[60:61]
	v_pk_mul_f32 v[172:173], v[172:173], v[62:63]
	v_pk_mul_f32 v[174:175], v[174:175], v[52:53]
	v_pk_mul_f32 v[176:177], v[176:177], v[54:55]
	v_cvt_pk_bf16_f32 v178, v170, v171
	v_cvt_pk_bf16_f32 v179, v172, v173
	v_cvt_pk_bf16_f32 v180, v174, v175
	v_cvt_pk_bf16_f32 v181, v176, v177
	global_store_dwordx4 v[192:193], v[178:181], off
	v_add_u32_e32 v196, 0xa0, v165
	v_mad_i64_i32 v[196:197], s[18:19], v196, s56, v[142:143]
	v_lshl_add_u64 v[196:197], v[196:197], 0, v[144:145]
	v_pk_mul_f32 v[170:171], v[48:49], s[68:69]
	v_pk_mul_f32 v[172:173], v[50:51], s[68:69]
	v_pk_mul_f32 v[174:175], v[40:41], s[68:69]
	v_pk_mul_f32 v[176:177], v[42:43], s[68:69]
	v_exp_f32_e32 v170, v170
	v_exp_f32_e32 v171, v171
	v_exp_f32_e32 v172, v172
	v_exp_f32_e32 v173, v173
	v_exp_f32_e32 v174, v174
	v_exp_f32_e32 v175, v175
	v_exp_f32_e32 v176, v176
	v_exp_f32_e32 v177, v177
	v_pk_add_f32 v[170:171], v[170:171], s[70:71]
	v_pk_add_f32 v[172:173], v[172:173], s[70:71]
	v_pk_add_f32 v[174:175], v[174:175], s[70:71]
	v_pk_add_f32 v[176:177], v[176:177], s[70:71]
	v_rcp_f32_e32 v170, v170
	v_rcp_f32_e32 v171, v171
	v_rcp_f32_e32 v172, v172
	v_rcp_f32_e32 v173, v173
	v_rcp_f32_e32 v174, v174
	v_rcp_f32_e32 v175, v175
	v_rcp_f32_e32 v176, v176
	v_rcp_f32_e32 v177, v177
	v_pk_mul_f32 v[170:171], v[48:49], v[170:171]
	v_pk_mul_f32 v[172:173], v[50:51], v[172:173]
	v_pk_mul_f32 v[174:175], v[40:41], v[174:175]
	v_pk_mul_f32 v[176:177], v[42:43], v[176:177]
	v_pk_mul_f32 v[170:171], v[170:171], v[44:45]
	v_pk_mul_f32 v[172:173], v[172:173], v[46:47]
	v_pk_mul_f32 v[174:175], v[174:175], v[36:37]
	v_pk_mul_f32 v[176:177], v[176:177], v[38:39]
	v_cvt_pk_bf16_f32 v182, v170, v171
	v_cvt_pk_bf16_f32 v183, v172, v173
	v_cvt_pk_bf16_f32 v184, v174, v175
	v_cvt_pk_bf16_f32 v185, v176, v177
	global_store_dwordx4 v[194:195], v[182:185], off
	v_add_u32_e32 v198, 0xb0, v165
	v_mad_i64_i32 v[198:199], s[18:19], v198, s56, v[142:143]
	v_lshl_add_u64 v[198:199], v[198:199], 0, v[144:145]
	s_mov_b64 s[18:19], -1
	v_pk_mul_f32 v[170:171], v[32:33], s[68:69]
	v_pk_mul_f32 v[172:173], v[34:35], s[68:69]
	v_pk_mul_f32 v[174:175], v[24:25], s[68:69]
	v_pk_mul_f32 v[176:177], v[26:27], s[68:69]
	v_exp_f32_e32 v170, v170
	v_exp_f32_e32 v171, v171
	v_exp_f32_e32 v172, v172
	v_exp_f32_e32 v173, v173
	v_exp_f32_e32 v174, v174
	v_exp_f32_e32 v175, v175
	v_exp_f32_e32 v176, v176
	v_exp_f32_e32 v177, v177
	v_pk_add_f32 v[170:171], v[170:171], s[70:71]
	v_pk_add_f32 v[172:173], v[172:173], s[70:71]
	v_pk_add_f32 v[174:175], v[174:175], s[70:71]
	v_pk_add_f32 v[176:177], v[176:177], s[70:71]
	v_rcp_f32_e32 v170, v170
	v_rcp_f32_e32 v171, v171
	v_rcp_f32_e32 v172, v172
	v_rcp_f32_e32 v173, v173
	v_rcp_f32_e32 v174, v174
	v_rcp_f32_e32 v175, v175
	v_rcp_f32_e32 v176, v176
	v_rcp_f32_e32 v177, v177
	v_pk_mul_f32 v[170:171], v[32:33], v[170:171]
	v_pk_mul_f32 v[172:173], v[34:35], v[172:173]
	v_pk_mul_f32 v[174:175], v[24:25], v[174:175]
	v_pk_mul_f32 v[176:177], v[26:27], v[176:177]
	v_pk_mul_f32 v[170:171], v[170:171], v[28:29]
	v_pk_mul_f32 v[172:173], v[172:173], v[30:31]
	v_pk_mul_f32 v[174:175], v[174:175], v[20:21]
	v_pk_mul_f32 v[176:177], v[176:177], v[22:23]
	v_cvt_pk_bf16_f32 v178, v170, v171
	v_cvt_pk_bf16_f32 v179, v172, v173
	v_cvt_pk_bf16_f32 v180, v174, v175
	v_cvt_pk_bf16_f32 v181, v176, v177
	global_store_dwordx4 v[196:197], v[178:181], off
	v_pk_mul_f32 v[170:171], v[16:17], s[68:69]
	v_pk_mul_f32 v[172:173], v[18:19], s[68:69]
	v_pk_mul_f32 v[174:175], v[8:9], s[68:69]
	v_pk_mul_f32 v[176:177], v[10:11], s[68:69]
	v_exp_f32_e32 v170, v170
	v_exp_f32_e32 v171, v171
	v_exp_f32_e32 v172, v172
	v_exp_f32_e32 v173, v173
	v_exp_f32_e32 v174, v174
	v_exp_f32_e32 v175, v175
	v_exp_f32_e32 v176, v176
	v_exp_f32_e32 v177, v177
	v_pk_add_f32 v[170:171], v[170:171], s[70:71]
	v_pk_add_f32 v[172:173], v[172:173], s[70:71]
	v_pk_add_f32 v[174:175], v[174:175], s[70:71]
	v_pk_add_f32 v[176:177], v[176:177], s[70:71]
	v_rcp_f32_e32 v170, v170
	v_rcp_f32_e32 v171, v171
	v_rcp_f32_e32 v172, v172
	v_rcp_f32_e32 v173, v173
	v_rcp_f32_e32 v174, v174
	v_rcp_f32_e32 v175, v175
	v_rcp_f32_e32 v176, v176
	v_rcp_f32_e32 v177, v177
	v_pk_mul_f32 v[170:171], v[16:17], v[170:171]
	v_pk_mul_f32 v[172:173], v[18:19], v[172:173]
	v_pk_mul_f32 v[174:175], v[8:9], v[174:175]
	v_pk_mul_f32 v[176:177], v[10:11], v[176:177]
	v_pk_mul_f32 v[170:171], v[170:171], v[12:13]
	v_pk_mul_f32 v[172:173], v[172:173], v[14:15]
	v_pk_mul_f32 v[174:175], v[174:175], v[4:5]
	v_pk_mul_f32 v[176:177], v[176:177], v[6:7]
	v_cvt_pk_bf16_f32 v182, v170, v171
	v_cvt_pk_bf16_f32 v183, v172, v173
	v_cvt_pk_bf16_f32 v184, v174, v175
	v_cvt_pk_bf16_f32 v185, v176, v177
	global_store_dwordx4 v[198:199], v[182:185], off
	s_cbranch_vccnz .LBB0_518
	s_andn2_b64 vcc, exec, s[6:7]
	s_cbranch_vccnz .LBB0_517
	s_barrier
	s_branch .LBB0_517
